# rope table loop: ten positions loads hoisted before the loop (register rotation), no vmcnt(0) in the loop
# speedup vs baseline: 1.0120x; 1.0010x over previous
; __global__ void __launch_bounds__(512, 2) hybrid_fwd(Args unused_args) {
;     ...
;       float* r16 = (float*)(ws + WS_ROPE16); float* r64 = (float*)(ws + WS_ROPE64);
;       for (int i = bid * 512 + tid; i < T * 40; i += G * 512) { const int row = i / 40, k = i % 40; const float pos = (float)a.pos[row];
;           const float inv = k < 8 ? exp2f(-(float)(2 * k) * (13.287712379549449f / 16.0f)) : exp2f(-(float)(2 * (k - 8)) * (13.287712379549449f / 64.0f));
;           const float ang = pos * inv; double ad = (double)ang; ad -= 6.283185307179586 * rint(ad * 0.15915494309189535); const float ar = (float)ad; const float sn = __sinf(ar), cs = __cosf(ar);
;           if (k < 8) { r16[(size_t)row * 16 + 2 * k] = cs; r16[(size_t)row * 16 + 2 * k + 1] = sn; } else { r64[(size_t)row * 64 + 2 * (k - 8)] = cs; r64[(size_t)row * 64 + 2 * (k - 8) + 1] = sn; } } }
.Lmy_xconv_done:
	v_lshl_add_u32 v2, s36, 9, v2
	s_mov_b32 s1, 0x140000
	v_cmp_gt_i32_e32 vcc, s1, v2
	s_and_saveexec_b64 s[2:3], vcc
	s_cbranch_execz .LBB0_595
	s_add_u32 s6, s28, 0x1b00000
	s_mov_b32 s10, 0x6dc9c883
	s_mov_b32 s12, 0x54442d18
	s_addc_u32 s7, s29, 0
	s_lshl_b32 s1, s30, 9
	v_lshlrev_b32_e32 v4, 1, v2
	s_lshl_b32 s14, s30, 10
	s_mov_b64 s[8:9], 0
	s_mov_b32 s15, 0x66666667
	s_movk_i32 s16, 0xffd8
	s_movk_i32 s17, 0xffb0
	s_mov_b32 s18, 0xc2fc0000
	v_not_b32_e32 v3, 63
	v_mov_b32_e32 v5, 0x42800000
	s_mov_b32 s11, 0x3fc45f30
	s_mov_b32 s13, 0xc01921fb
	v_mov_b32_e32 v12, 0
	s_mov_b32 s19, 0x13ffff
	s_cmpk_eq_u32 s30, 0x100
	s_cbranch_scc0 .Lmy_rope_go
	v_mov_b32_e32 v110, v2
	v_mul_hi_i32 v111, v110, s15
	v_lshrrev_b32_e32 v113, 31, v111
	v_ashrrev_i32_e32 v111, 4, v111
	v_add_u32_e32 v112, v111, v113
	v_ashrrev_i32_e32 v113, 31, v112
	v_lshl_add_u64 v[126:127], v[112:113], 2, s[26:27]
	global_load_dword v114, v[126:127], off
	v_add_u32_e32 v110, s1, v110
	v_mul_hi_i32 v111, v110, s15
	v_lshrrev_b32_e32 v113, 31, v111
	v_ashrrev_i32_e32 v111, 4, v111
	v_add_u32_e32 v112, v111, v113
	v_ashrrev_i32_e32 v113, 31, v112
	v_lshl_add_u64 v[126:127], v[112:113], 2, s[26:27]
	global_load_dword v115, v[126:127], off
	v_add_u32_e32 v110, s1, v110
	v_mul_hi_i32 v111, v110, s15
	v_lshrrev_b32_e32 v113, 31, v111
	v_ashrrev_i32_e32 v111, 4, v111
	v_add_u32_e32 v112, v111, v113
	v_ashrrev_i32_e32 v113, 31, v112
	v_lshl_add_u64 v[126:127], v[112:113], 2, s[26:27]
	global_load_dword v116, v[126:127], off
	v_add_u32_e32 v110, s1, v110
	v_mul_hi_i32 v111, v110, s15
	v_lshrrev_b32_e32 v113, 31, v111
	v_ashrrev_i32_e32 v111, 4, v111
	v_add_u32_e32 v112, v111, v113
	v_ashrrev_i32_e32 v113, 31, v112
	v_lshl_add_u64 v[126:127], v[112:113], 2, s[26:27]
	global_load_dword v117, v[126:127], off
	v_add_u32_e32 v110, s1, v110
	v_mul_hi_i32 v111, v110, s15
	v_lshrrev_b32_e32 v113, 31, v111
	v_ashrrev_i32_e32 v111, 4, v111
	v_add_u32_e32 v112, v111, v113
	v_ashrrev_i32_e32 v113, 31, v112
	v_lshl_add_u64 v[126:127], v[112:113], 2, s[26:27]
	global_load_dword v118, v[126:127], off
	v_add_u32_e32 v110, s1, v110
	v_mul_hi_i32 v111, v110, s15
	v_lshrrev_b32_e32 v113, 31, v111
	v_ashrrev_i32_e32 v111, 4, v111
	v_add_u32_e32 v112, v111, v113
	v_ashrrev_i32_e32 v113, 31, v112
	v_lshl_add_u64 v[126:127], v[112:113], 2, s[26:27]
	global_load_dword v119, v[126:127], off
	v_add_u32_e32 v110, s1, v110
	v_mul_hi_i32 v111, v110, s15
	v_lshrrev_b32_e32 v113, 31, v111
	v_ashrrev_i32_e32 v111, 4, v111
	v_add_u32_e32 v112, v111, v113
	v_ashrrev_i32_e32 v113, 31, v112
	v_lshl_add_u64 v[126:127], v[112:113], 2, s[26:27]
	global_load_dword v120, v[126:127], off
	v_add_u32_e32 v110, s1, v110
	v_mul_hi_i32 v111, v110, s15
	v_lshrrev_b32_e32 v113, 31, v111
	v_ashrrev_i32_e32 v111, 4, v111
	v_add_u32_e32 v112, v111, v113
	v_ashrrev_i32_e32 v113, 31, v112
	v_lshl_add_u64 v[126:127], v[112:113], 2, s[26:27]
	global_load_dword v121, v[126:127], off
	v_add_u32_e32 v110, s1, v110
	v_mul_hi_i32 v111, v110, s15
	v_lshrrev_b32_e32 v113, 31, v111
	v_ashrrev_i32_e32 v111, 4, v111
	v_add_u32_e32 v112, v111, v113
	v_ashrrev_i32_e32 v113, 31, v112
	v_lshl_add_u64 v[126:127], v[112:113], 2, s[26:27]
	global_load_dword v122, v[126:127], off
	v_add_u32_e32 v110, s1, v110
	v_mul_hi_i32 v111, v110, s15
	v_lshrrev_b32_e32 v113, 31, v111
	v_ashrrev_i32_e32 v111, 4, v111
	v_add_u32_e32 v112, v111, v113
	v_ashrrev_i32_e32 v113, 31, v112
	v_lshl_add_u64 v[126:127], v[112:113], 2, s[26:27]
	global_load_dword v123, v[126:127], off
	s_waitcnt vmcnt(0)

; __global__ void __launch_bounds__(512, 2) hybrid_fwd(Args unused_args) {
;     ...
;       for (int i = bid * 512 + tid; i < T * 40; i += G * 512) { const int row = i / 40, k = i % 40; const float pos = (float)a.pos[row];
;           const float inv = k < 8 ? exp2f(-(float)(2 * k) * (13.287712379549449f / 16.0f)) : exp2f(-(float)(2 * (k - 8)) * (13.287712379549449f / 64.0f));
;           const float ang = pos * inv; double ad = (double)ang; ad -= 6.283185307179586 * rint(ad * 0.15915494309189535); const float ar = (float)ad; const float sn = __sinf(ar), cs = __cosf(ar);
;           if (k < 8) { r16[(size_t)row * 16 + 2 * k] = cs; r16[(size_t)row * 16 + 2 * k + 1] = sn; } else { r64[(size_t)row * 64 + 2 * (k - 8)] = cs; r64[(size_t)row * 64 + 2 * (k - 8) + 1] = sn; } } }
.LBB0_587:
	v_mul_hi_i32 v6, v2, s15
	v_lshrrev_b32_e32 v7, 31, v6
	v_ashrrev_i32_e32 v6, 4, v6
	v_add_u32_e32 v6, v6, v7
	v_ashrrev_i32_e32 v7, 31, v6
	v_lshl_add_u64 v[8:9], v[6:7], 2, s[26:27]
	s_cmpk_eq_u32 s30, 0x100
	s_cbranch_scc1 .Lmy_rope_fast
	global_load_dword v10, v[8:9], off
	s_waitcnt vmcnt(0)
	s_branch .Lmy_rope_join
.Lmy_rope_fast:
	v_mov_b32_e32 v10, v114
	v_mov_b32_e32 v114, v115
	v_mov_b32_e32 v115, v116
	v_mov_b32_e32 v116, v117
	v_mov_b32_e32 v117, v118
	v_mov_b32_e32 v118, v119
	v_mov_b32_e32 v119, v120
	v_mov_b32_e32 v120, v121
	v_mov_b32_e32 v121, v122
	v_mov_b32_e32 v122, v123
.Lmy_rope_join:
	v_mad_u64_u32 v[8:9], s[4:5], v6, s16, v[2:3]
	v_cmp_lt_i32_e32 vcc, 7, v8
	v_mad_u64_u32 v[8:9], s[4:5], v6, s17, v[4:5]
	s_and_saveexec_b64 s[4:5], vcc
	s_xor_b64 s[4:5], exec, s[4:5]
	v_add_u32_e32 v9, -16, v8
	v_cvt_f32_u32_e32 v9, v9
	v_mul_f32_e32 v9, 0xbe549a78, v9
	s_andn2_saveexec_b64 s[4:5], s[4:5]
	v_cvt_f32_i32_e32 v9, v8
	v_mul_f32_e32 v9, 0xbf549a78, v9
	s_or_b64 exec, exec, s[4:5]
	v_cmp_gt_f32_e64 s[4:5], s18, v9
	s_nop 0
	v_cvt_f32_i32_e32 v10, v10
	v_cndmask_b32_e64 v13, 0, v5, s[4:5]
	v_add_f32_e32 v9, v9, v13
	v_exp_f32_e32 v9, v9
	v_cndmask_b32_e64 v11, 0, v3, s[4:5]
	v_ldexp_f32 v9, v9, v11
	v_mul_f32_e32 v9, v9, v10
	v_cvt_f64_f32_e32 v[10:11], v9
	v_mul_f64 v[14:15], v[10:11], s[10:11]
	v_rndne_f64_e32 v[14:15], v[14:15]
	v_fmac_f64_e32 v[10:11], s[12:13], v[14:15]
	v_cvt_f32_f64_e32 v9, v[10:11]
	v_mul_f32_e32 v9, 0.15915494, v9
	v_sin_f32_e32 v11, v9
	v_cos_f32_e32 v10, v9
	s_and_saveexec_b64 s[4:5], vcc
	s_xor_b64 s[4:5], exec, s[4:5]
	s_cbranch_execz .LBB0_593
	v_lshlrev_b64 v[6:7], 8, v[6:7]
	v_lshl_add_u64 v[6:7], s[28:29], 0, v[6:7]
	v_mov_b32_e32 v9, v12
	v_lshl_add_u64 v[6:7], v[8:9], 2, v[6:7]
	v_add_co_u32_e32 v6, vcc, 0x1cff000, v6
	s_nop 1
	v_addc_co_u32_e32 v7, vcc, 0, v7, vcc
	global_store_dwordx2 v[6:7], v[10:11], off offset:4032
